# P1 epilogue H-tile stores use the sc1 nt cache policy (write-through, streaming) instead of the default
# speedup vs baseline: 1.0027x; 1.0015x over previous
.LBB0_108:
	v_lshl_add_u32 v146, s46, 8, v152
	s_cmpk_lg_i32 s18, 0x4c
	s_mov_b64 s[0:1], -1
	v_readlane_b32 s61, v254, 34
	s_cbranch_scc0 .LBB0_115
	s_cmp_lt_i32 s18, 60
	s_cbranch_scc0 .LBB0_111
	v_lshl_add_u32 v147, s18, 8, v154
	v_ashrrev_i32_e32 v148, 8, v147
	s_and_b32 s0, s18, -4
	v_ashrrev_i32_e32 v149, 31, v148
	s_cmp_eq_u32 s0, 36
	v_lshlrev_b64 v[148:149], 22, v[148:149]
	v_ashrrev_i32_e32 v147, 31, v146
	v_lshl_add_u64 v[150:151], s[14:15], 0, v[148:149]
	v_lshlrev_b64 v[148:149], 9, v[146:147]
	v_pk_mul_f32 v[156:157], v[72:73], s[26:27] op_sel_hi:[1,0]
	v_pk_mul_f32 v[158:159], v[70:71], s[26:27] op_sel_hi:[1,0]
	v_pk_mul_f32 v[160:161], v[68:69], s[26:27] op_sel_hi:[1,0]
	v_pk_mul_f32 v[162:163], v[66:67], s[26:27] op_sel_hi:[1,0]
	s_cselect_b64 vcc, -1, 0
	v_lshl_add_u64 v[148:149], v[150:151], 0, v[148:149]
	v_cndmask_b32_e32 v147, v73, v157, vcc
	v_cndmask_b32_e32 v157, v72, v156, vcc
	v_cndmask_b32_e32 v156, v71, v159, vcc
	v_cndmask_b32_e32 v158, v70, v158, vcc
	v_cndmask_b32_e32 v159, v69, v161, vcc
	v_cndmask_b32_e32 v160, v68, v160, vcc
	v_cndmask_b32_e32 v161, v67, v163, vcc
	v_cndmask_b32_e32 v162, v66, v162, vcc
	v_lshl_add_u64 v[148:149], v[148:149], 0, v[0:1]
	v_cvt_pk_bf16_f32 v156, v158, v156
	v_cvt_pk_bf16_f32 v157, v157, v147
	v_cvt_pk_bf16_f32 v158, v162, v161
	v_cvt_pk_bf16_f32 v159, v160, v159
	global_store_dwordx4 v[148:149], v[156:159], off sc1 nt
	v_pk_mul_f32 v[160:161], v[124:125], s[26:27] op_sel_hi:[1,0]
	v_pk_mul_f32 v[162:163], v[122:123], s[26:27] op_sel_hi:[1,0]
	v_pk_mul_f32 v[156:157], v[128:129], s[26:27] op_sel_hi:[1,0]
	v_pk_mul_f32 v[158:159], v[126:127], s[26:27] op_sel_hi:[1,0]
	v_cndmask_b32_e32 v147, v129, v157, vcc
	v_cndmask_b32_e32 v157, v128, v156, vcc
	v_cndmask_b32_e32 v156, v127, v159, vcc
	v_cndmask_b32_e32 v158, v126, v158, vcc
	v_cndmask_b32_e32 v159, v125, v161, vcc
	v_cndmask_b32_e32 v160, v124, v160, vcc
	v_cndmask_b32_e32 v161, v123, v163, vcc
	v_cndmask_b32_e32 v162, v122, v162, vcc
	v_cvt_pk_bf16_f32 v156, v158, v156
	v_cvt_pk_bf16_f32 v157, v157, v147
	v_cvt_pk_bf16_f32 v158, v162, v161
	v_cvt_pk_bf16_f32 v159, v160, v159
	global_store_dwordx4 v[148:149], v[156:159], off offset:256 sc1 nt
	v_pk_mul_f32 v[162:163], v[60:61], s[26:27] op_sel_hi:[1,0]
	v_pk_mul_f32 v[164:165], v[58:59], s[26:27] op_sel_hi:[1,0]
	v_or_b32_e32 v156, 16, v146
	v_ashrrev_i32_e32 v157, 31, v156
	v_lshlrev_b64 v[156:157], 9, v[156:157]
	v_lshl_add_u64 v[156:157], v[150:151], 0, v[156:157]
	v_lshl_add_u64 v[160:161], v[156:157], 0, v[0:1]
	v_pk_mul_f32 v[156:157], v[64:65], s[26:27] op_sel_hi:[1,0]
	v_pk_mul_f32 v[158:159], v[62:63], s[26:27] op_sel_hi:[1,0]
	v_cndmask_b32_e32 v147, v65, v157, vcc
	v_cndmask_b32_e32 v157, v64, v156, vcc
	v_cndmask_b32_e32 v156, v63, v159, vcc
	v_cndmask_b32_e32 v158, v62, v158, vcc
	v_cndmask_b32_e32 v159, v61, v163, vcc
	v_cndmask_b32_e32 v162, v60, v162, vcc
	v_cndmask_b32_e32 v163, v59, v165, vcc
	v_cndmask_b32_e32 v164, v58, v164, vcc
	v_cvt_pk_bf16_f32 v156, v158, v156
	v_cvt_pk_bf16_f32 v157, v157, v147
	v_cvt_pk_bf16_f32 v158, v164, v163
	v_cvt_pk_bf16_f32 v159, v162, v159
	global_store_dwordx4 v[160:161], v[156:159], off sc1 nt
	v_pk_mul_f32 v[162:163], v[116:117], s[26:27] op_sel_hi:[1,0]
	v_pk_mul_f32 v[164:165], v[114:115], s[26:27] op_sel_hi:[1,0]
	v_pk_mul_f32 v[156:157], v[120:121], s[26:27] op_sel_hi:[1,0]
	v_pk_mul_f32 v[158:159], v[118:119], s[26:27] op_sel_hi:[1,0]
	v_cndmask_b32_e32 v147, v121, v157, vcc
	v_cndmask_b32_e32 v157, v120, v156, vcc
	v_cndmask_b32_e32 v156, v119, v159, vcc
	v_cndmask_b32_e32 v158, v118, v158, vcc
	v_cndmask_b32_e32 v159, v117, v163, vcc
	v_cndmask_b32_e32 v162, v116, v162, vcc
	v_cndmask_b32_e32 v163, v115, v165, vcc
	v_cndmask_b32_e32 v164, v114, v164, vcc
	v_cvt_pk_bf16_f32 v156, v158, v156
	v_cvt_pk_bf16_f32 v157, v157, v147
	v_cvt_pk_bf16_f32 v158, v164, v163
	v_cvt_pk_bf16_f32 v159, v162, v159
	global_store_dwordx4 v[160:161], v[156:159], off offset:256 sc1 nt
	v_pk_mul_f32 v[162:163], v[48:49], s[26:27] op_sel_hi:[1,0]
	v_pk_mul_f32 v[164:165], v[46:47], s[26:27] op_sel_hi:[1,0]
	v_or_b32_e32 v156, 32, v146
	v_ashrrev_i32_e32 v157, 31, v156
	v_lshlrev_b64 v[156:157], 9, v[156:157]
	v_lshl_add_u64 v[156:157], v[150:151], 0, v[156:157]
	v_lshl_add_u64 v[160:161], v[156:157], 0, v[0:1]
	v_pk_mul_f32 v[156:157], v[52:53], s[26:27] op_sel_hi:[1,0]
	v_pk_mul_f32 v[158:159], v[50:51], s[26:27] op_sel_hi:[1,0]
	v_cndmask_b32_e32 v147, v53, v157, vcc
	v_cndmask_b32_e32 v157, v52, v156, vcc
	v_cndmask_b32_e32 v156, v51, v159, vcc
	v_cndmask_b32_e32 v158, v50, v158, vcc
	v_cndmask_b32_e32 v159, v49, v163, vcc
	v_cndmask_b32_e32 v162, v48, v162, vcc
	v_cndmask_b32_e32 v163, v47, v165, vcc
	v_cndmask_b32_e32 v164, v46, v164, vcc
	v_cvt_pk_bf16_f32 v156, v158, v156
	v_cvt_pk_bf16_f32 v157, v157, v147
	v_cvt_pk_bf16_f32 v158, v164, v163
	v_cvt_pk_bf16_f32 v159, v162, v159
	global_store_dwordx4 v[160:161], v[156:159], off sc1 nt
	v_pk_mul_f32 v[162:163], v[108:109], s[26:27] op_sel_hi:[1,0]
	v_pk_mul_f32 v[164:165], v[106:107], s[26:27] op_sel_hi:[1,0]
	v_pk_mul_f32 v[156:157], v[112:113], s[26:27] op_sel_hi:[1,0]
	v_pk_mul_f32 v[158:159], v[110:111], s[26:27] op_sel_hi:[1,0]
	v_cndmask_b32_e32 v147, v113, v157, vcc
	v_cndmask_b32_e32 v157, v112, v156, vcc
	v_cndmask_b32_e32 v156, v111, v159, vcc
	v_cndmask_b32_e32 v158, v110, v158, vcc
	v_cndmask_b32_e32 v159, v109, v163, vcc
	v_cndmask_b32_e32 v162, v108, v162, vcc
	v_cndmask_b32_e32 v163, v107, v165, vcc
	v_cndmask_b32_e32 v164, v106, v164, vcc
	v_cvt_pk_bf16_f32 v156, v158, v156
	v_cvt_pk_bf16_f32 v157, v157, v147
	v_cvt_pk_bf16_f32 v158, v164, v163
	v_cvt_pk_bf16_f32 v159, v162, v159
	global_store_dwordx4 v[160:161], v[156:159], off offset:256 sc1 nt
	v_pk_mul_f32 v[160:161], v[40:41], s[26:27] op_sel_hi:[1,0]
	v_pk_mul_f32 v[162:163], v[38:39], s[26:27] op_sel_hi:[1,0]
	v_or_b32_e32 v156, 48, v146
	v_ashrrev_i32_e32 v157, 31, v156
	v_lshlrev_b64 v[156:157], 9, v[156:157]
	v_lshl_add_u64 v[150:151], v[150:151], 0, v[156:157]
	v_pk_mul_f32 v[156:157], v[44:45], s[26:27] op_sel_hi:[1,0]
	v_pk_mul_f32 v[158:159], v[42:43], s[26:27] op_sel_hi:[1,0]
	v_cndmask_b32_e32 v147, v45, v157, vcc
	v_cndmask_b32_e32 v157, v44, v156, vcc
	v_cndmask_b32_e32 v156, v43, v159, vcc
	v_cndmask_b32_e32 v158, v42, v158, vcc
	v_cndmask_b32_e32 v159, v41, v161, vcc
	v_cndmask_b32_e32 v160, v40, v160, vcc
	v_cndmask_b32_e32 v161, v39, v163, vcc
	v_cndmask_b32_e32 v162, v38, v162, vcc
	v_lshl_add_u64 v[150:151], v[150:151], 0, v[0:1]
	v_cvt_pk_bf16_f32 v156, v158, v156
	v_cvt_pk_bf16_f32 v157, v157, v147
	v_cvt_pk_bf16_f32 v158, v162, v161
	v_cvt_pk_bf16_f32 v159, v160, v159
	global_store_dwordx4 v[150:151], v[156:159], off sc1 nt
	v_pk_mul_f32 v[160:161], v[100:101], s[26:27] op_sel_hi:[1,0]
	v_pk_mul_f32 v[162:163], v[98:99], s[26:27] op_sel_hi:[1,0]
	v_pk_mul_f32 v[156:157], v[104:105], s[26:27] op_sel_hi:[1,0]
	v_pk_mul_f32 v[158:159], v[102:103], s[26:27] op_sel_hi:[1,0]
	v_cndmask_b32_e32 v147, v105, v157, vcc
	v_cndmask_b32_e32 v157, v104, v156, vcc
	v_cndmask_b32_e32 v156, v103, v159, vcc
	v_cndmask_b32_e32 v158, v102, v158, vcc
	v_cndmask_b32_e32 v159, v101, v161, vcc
	v_cndmask_b32_e32 v160, v100, v160, vcc
	v_cndmask_b32_e32 v161, v99, v163, vcc
	v_cndmask_b32_e32 v162, v98, v162, vcc
	v_cvt_pk_bf16_f32 v156, v158, v156
	v_cvt_pk_bf16_f32 v157, v157, v147
	v_cvt_pk_bf16_f32 v158, v162, v161
	v_cvt_pk_bf16_f32 v159, v160, v159
	global_store_dwordx4 v[150:151], v[156:159], off offset:256 sc1 nt
	s_mov_b64 s[0:1], 0x10000
	v_pk_mul_f32 v[160:161], v[28:29], s[26:27] op_sel_hi:[1,0]
	v_pk_mul_f32 v[156:157], v[32:33], s[26:27] op_sel_hi:[1,0]
	v_pk_mul_f32 v[158:159], v[30:31], s[26:27] op_sel_hi:[1,0]
	v_lshl_add_u64 v[150:151], v[148:149], 0, s[0:1]
	v_pk_mul_f32 v[162:163], v[26:27], s[26:27] op_sel_hi:[1,0]
	v_cndmask_b32_e32 v147, v33, v157, vcc
	v_cndmask_b32_e32 v157, v32, v156, vcc
	v_cndmask_b32_e32 v156, v31, v159, vcc
	v_cndmask_b32_e32 v159, v29, v161, vcc
	v_cndmask_b32_e32 v160, v28, v160, vcc
	s_mov_b32 s0, 0x10000
	v_cndmask_b32_e32 v158, v30, v158, vcc
	v_cndmask_b32_e32 v161, v27, v163, vcc
	v_cndmask_b32_e32 v162, v26, v162, vcc
	v_cvt_pk_bf16_f32 v159, v160, v159
	v_add_co_u32_e64 v160, s[0:1], s0, v148
	v_cvt_pk_bf16_f32 v156, v158, v156
	v_cvt_pk_bf16_f32 v157, v157, v147
	v_cvt_pk_bf16_f32 v158, v162, v161
	v_addc_co_u32_e64 v161, s[0:1], 0, v149, s[0:1]
	global_store_dwordx4 v[160:161], v[156:159], off sc1 nt
	v_pk_mul_f32 v[160:161], v[92:93], s[26:27] op_sel_hi:[1,0]
	v_pk_mul_f32 v[162:163], v[90:91], s[26:27] op_sel_hi:[1,0]
	v_pk_mul_f32 v[156:157], v[96:97], s[26:27] op_sel_hi:[1,0]
	v_pk_mul_f32 v[158:159], v[94:95], s[26:27] op_sel_hi:[1,0]
	v_cndmask_b32_e32 v147, v97, v157, vcc
	v_cndmask_b32_e32 v157, v96, v156, vcc
	v_cndmask_b32_e32 v156, v95, v159, vcc
	v_cndmask_b32_e32 v158, v94, v158, vcc
	v_cndmask_b32_e32 v159, v93, v161, vcc
	v_cndmask_b32_e32 v160, v92, v160, vcc
	v_cndmask_b32_e32 v161, v91, v163, vcc
	v_cndmask_b32_e32 v162, v90, v162, vcc
	v_cvt_pk_bf16_f32 v156, v158, v156
	v_cvt_pk_bf16_f32 v157, v157, v147
	v_cvt_pk_bf16_f32 v158, v162, v161
	v_cvt_pk_bf16_f32 v159, v160, v159
	global_store_dwordx4 v[150:151], v[156:159], off offset:256 sc1 nt
	s_mov_b64 s[0:1], 0x12000
	v_pk_mul_f32 v[160:161], v[20:21], s[26:27] op_sel_hi:[1,0]
	v_pk_mul_f32 v[156:157], v[24:25], s[26:27] op_sel_hi:[1,0]
	v_pk_mul_f32 v[158:159], v[22:23], s[26:27] op_sel_hi:[1,0]
	v_lshl_add_u64 v[150:151], v[148:149], 0, s[0:1]
	v_pk_mul_f32 v[162:163], v[18:19], s[26:27] op_sel_hi:[1,0]
	v_cndmask_b32_e32 v147, v25, v157, vcc
	v_cndmask_b32_e32 v157, v24, v156, vcc
	v_cndmask_b32_e32 v156, v23, v159, vcc
	v_cndmask_b32_e32 v159, v21, v161, vcc
	v_cndmask_b32_e32 v160, v20, v160, vcc
	s_mov_b32 s0, 0x12000
	v_cndmask_b32_e32 v158, v22, v158, vcc
	v_cndmask_b32_e32 v161, v19, v163, vcc
	v_cndmask_b32_e32 v162, v18, v162, vcc
	v_cvt_pk_bf16_f32 v159, v160, v159
	v_add_co_u32_e64 v160, s[0:1], s0, v148
	v_cvt_pk_bf16_f32 v156, v158, v156
	v_cvt_pk_bf16_f32 v157, v157, v147
	v_cvt_pk_bf16_f32 v158, v162, v161
	v_addc_co_u32_e64 v161, s[0:1], 0, v149, s[0:1]
	global_store_dwordx4 v[160:161], v[156:159], off sc1 nt
	v_pk_mul_f32 v[160:161], v[84:85], s[26:27] op_sel_hi:[1,0]
	v_pk_mul_f32 v[162:163], v[82:83], s[26:27] op_sel_hi:[1,0]
	v_pk_mul_f32 v[156:157], v[88:89], s[26:27] op_sel_hi:[1,0]
	v_pk_mul_f32 v[158:159], v[86:87], s[26:27] op_sel_hi:[1,0]
	v_cndmask_b32_e32 v147, v89, v157, vcc
	v_cndmask_b32_e32 v157, v88, v156, vcc
	v_cndmask_b32_e32 v156, v87, v159, vcc
	v_cndmask_b32_e32 v158, v86, v158, vcc
	v_cndmask_b32_e32 v159, v85, v161, vcc
	v_cndmask_b32_e32 v160, v84, v160, vcc
	v_cndmask_b32_e32 v161, v83, v163, vcc
	v_cndmask_b32_e32 v162, v82, v162, vcc
	v_cvt_pk_bf16_f32 v156, v158, v156
	v_cvt_pk_bf16_f32 v157, v157, v147
	v_cvt_pk_bf16_f32 v158, v162, v161
	v_cvt_pk_bf16_f32 v159, v160, v159
	global_store_dwordx4 v[150:151], v[156:159], off offset:256 sc1 nt
	s_mov_b64 s[0:1], 0x14000
	v_pk_mul_f32 v[160:161], v[12:13], s[26:27] op_sel_hi:[1,0]
	v_pk_mul_f32 v[156:157], v[16:17], s[26:27] op_sel_hi:[1,0]
	v_pk_mul_f32 v[158:159], v[14:15], s[26:27] op_sel_hi:[1,0]
	v_lshl_add_u64 v[150:151], v[148:149], 0, s[0:1]
	v_pk_mul_f32 v[162:163], v[10:11], s[26:27] op_sel_hi:[1,0]
	v_cndmask_b32_e32 v147, v17, v157, vcc
	v_cndmask_b32_e32 v157, v16, v156, vcc
	v_cndmask_b32_e32 v156, v15, v159, vcc
	v_cndmask_b32_e32 v159, v13, v161, vcc
	v_cndmask_b32_e32 v160, v12, v160, vcc
	s_mov_b32 s0, 0x14000
	v_cndmask_b32_e32 v158, v14, v158, vcc
	v_cndmask_b32_e32 v161, v11, v163, vcc
	v_cndmask_b32_e32 v162, v10, v162, vcc
	v_cvt_pk_bf16_f32 v159, v160, v159
	v_add_co_u32_e64 v160, s[0:1], s0, v148
	v_cvt_pk_bf16_f32 v156, v158, v156
	v_cvt_pk_bf16_f32 v157, v157, v147
	v_cvt_pk_bf16_f32 v158, v162, v161
	v_addc_co_u32_e64 v161, s[0:1], 0, v149, s[0:1]
	global_store_dwordx4 v[160:161], v[156:159], off sc1 nt
	v_pk_mul_f32 v[160:161], v[76:77], s[26:27] op_sel_hi:[1,0]
	v_pk_mul_f32 v[162:163], v[74:75], s[26:27] op_sel_hi:[1,0]
	v_pk_mul_f32 v[156:157], v[80:81], s[26:27] op_sel_hi:[1,0]
	v_pk_mul_f32 v[158:159], v[78:79], s[26:27] op_sel_hi:[1,0]
	v_cndmask_b32_e32 v147, v81, v157, vcc
	v_cndmask_b32_e32 v157, v80, v156, vcc
	v_cndmask_b32_e32 v156, v79, v159, vcc
	v_cndmask_b32_e32 v158, v78, v158, vcc
	v_cndmask_b32_e32 v159, v77, v161, vcc
	v_cndmask_b32_e32 v160, v76, v160, vcc
	v_cndmask_b32_e32 v161, v75, v163, vcc
	v_cndmask_b32_e32 v162, v74, v162, vcc
	v_cvt_pk_bf16_f32 v156, v158, v156
	v_cvt_pk_bf16_f32 v157, v157, v147
	v_cvt_pk_bf16_f32 v158, v162, v161
	v_cvt_pk_bf16_f32 v159, v160, v159
	s_mov_b64 s[0:1], 0x16000
	global_store_dwordx4 v[150:151], v[156:159], off offset:256 sc1 nt
	v_lshl_add_u64 v[160:161], v[148:149], 0, s[0:1]
	v_pk_mul_f32 v[150:151], v[8:9], s[26:27] op_sel_hi:[1,0]
	v_pk_mul_f32 v[156:157], v[6:7], s[26:27] op_sel_hi:[1,0]
	v_pk_mul_f32 v[158:159], v[4:5], s[26:27] op_sel_hi:[1,0]
	v_pk_mul_f32 v[162:163], v[2:3], s[26:27] op_sel_hi:[1,0]
	s_mov_b32 s0, 0x16000
	v_cndmask_b32_e32 v147, v9, v151, vcc
	v_cndmask_b32_e32 v150, v8, v150, vcc
	v_cndmask_b32_e32 v151, v7, v157, vcc
	v_cndmask_b32_e32 v156, v6, v156, vcc
	v_cndmask_b32_e32 v159, v5, v159, vcc
	v_cndmask_b32_e32 v164, v4, v158, vcc
	v_cndmask_b32_e32 v158, v3, v163, vcc
	v_cndmask_b32_e32 v162, v2, v162, vcc
	v_add_co_u32_e64 v148, s[0:1], s0, v148
	v_cvt_pk_bf16_f32 v156, v156, v151
	v_cvt_pk_bf16_f32 v157, v150, v147
	v_cvt_pk_bf16_f32 v158, v162, v158
	v_cvt_pk_bf16_f32 v159, v164, v159
	v_addc_co_u32_e64 v149, s[0:1], 0, v149, s[0:1]
	global_store_dwordx4 v[148:149], v[156:159], off sc1 nt
	v_pk_mul_f32 v[148:149], v[56:57], s[26:27] op_sel_hi:[1,0]
	v_pk_mul_f32 v[150:151], v[54:55], s[26:27] op_sel_hi:[1,0]
	v_pk_mul_f32 v[156:157], v[36:37], s[26:27] op_sel_hi:[1,0]
	v_pk_mul_f32 v[158:159], v[34:35], s[26:27] op_sel_hi:[1,0]
	v_cndmask_b32_e32 v147, v57, v149, vcc
	v_cndmask_b32_e32 v149, v56, v148, vcc
	v_cndmask_b32_e32 v148, v55, v151, vcc
	v_cndmask_b32_e32 v150, v54, v150, vcc
	v_cndmask_b32_e32 v151, v37, v157, vcc
	v_cndmask_b32_e32 v156, v36, v156, vcc
	v_cndmask_b32_e32 v157, v35, v159, vcc
	v_cndmask_b32_e32 v158, v34, v158, vcc
	v_cvt_pk_bf16_f32 v148, v150, v148
	v_cvt_pk_bf16_f32 v149, v149, v147
	v_cvt_pk_bf16_f32 v150, v158, v157
	v_cvt_pk_bf16_f32 v151, v156, v151
	global_store_dwordx4 v[160:161], v[148:151], off offset:256 sc1 nt
	s_mov_b64 s[0:1], 0
.LBB0_111:
	s_andn2_b64 vcc, exec, s[0:1]
	s_cbranch_vccnz .LBB0_113
	v_mul_f32_e32 v147, 0xbfb8aa3b, v70
	v_exp_f32_e32 v147, v147
	v_mul_f32_e32 v148, 0xbfb8aa3b, v71
	v_exp_f32_e32 v148, v148
	v_mul_f32_e32 v149, 0xbfb8aa3b, v73
	v_add_f32_e32 v147, 1.0, v147
	v_rcp_f32_e32 v156, v147
	v_add_f32_e32 v147, 1.0, v148
	v_mul_f32_e32 v148, 0xbfb8aa3b, v72
	v_exp_f32_e32 v148, v148
	v_exp_f32_e32 v149, v149
	v_rcp_f32_e32 v158, v147
	s_ashr_i32 s47, s46, 31
	v_add_f32_e32 v147, 1.0, v148
	v_mul_f32_e32 v148, 0xbfb8aa3b, v66
	v_exp_f32_e32 v148, v148
	v_rcp_f32_e32 v160, v147
	v_add_f32_e32 v147, 1.0, v149
	v_mul_f32_e32 v149, 0xbfb8aa3b, v67
	v_exp_f32_e32 v149, v149
	s_lshl_b64 s[0:1], s[18:19], 22
	v_rcp_f32_e32 v162, v147
	v_add_f32_e32 v147, 1.0, v148
	v_mul_f32_e32 v148, 0xbfb8aa3b, v68
	s_add_u32 s18, s14, s0
	v_exp_f32_e32 v148, v148
	s_addc_u32 s30, s15, s1
	s_lshl_b64 s[0:1], s[46:47], 17
	v_rcp_f32_e32 v157, v147
	v_add_f32_e32 v147, 1.0, v149
	v_mul_f32_e32 v149, 0xbfb8aa3b, v69
	s_add_u32 s0, s18, s0
	v_exp_f32_e32 v149, v149
	s_addc_u32 s1, s30, s1
	s_add_u32 s0, s0, s20
	v_rcp_f32_e32 v159, v147
	v_add_f32_e32 v147, 1.0, v148
	s_addc_u32 s1, s1, s21
	v_rcp_f32_e32 v161, v147
	v_lshl_add_u64 v[150:151], s[0:1], 0, v[138:139]
	v_add_f32_e32 v147, 1.0, v149
	s_mov_b32 s0, 0x43000000
	v_rcp_f32_e32 v163, v147
	v_mov_b64_e32 v[148:149], s[0:1]
	s_mov_b32 s0, 0x3f7f0000
	v_pk_fma_f32 v[156:157], v[156:157], s[0:1], v[148:149] op_sel_hi:[1,0,0]
	v_pk_fma_f32 v[158:159], v[158:159], s[0:1], v[148:149] op_sel_hi:[1,0,0]
	v_pk_fma_f32 v[160:161], v[160:161], s[0:1], v[148:149] op_sel_hi:[1,0,0]
	v_lshrrev_b32_e32 v147, 8, v157
	v_and_b32_e32 v157, 0xff00, v159
	v_or_b32_sdwa v147, v147, v157 dst_sel:DWORD dst_unused:UNUSED_PAD src0_sel:BYTE_0 src1_sel:DWORD
	v_lshlrev_b32_e32 v157, 8, v161
	v_pk_fma_f32 v[162:163], v[162:163], s[0:1], v[148:149] op_sel_hi:[1,0,0]
	v_and_b32_e32 v157, 0xff0000, v157
	v_or_b32_e32 v147, v147, v157
	v_lshlrev_b32_e32 v157, 16, v163
	v_mul_f32_e32 v127, 0xbfb8aa3b, v127
	v_and_b32_e32 v157, 0xff000000, v157
	v_exp_f32_e32 v127, v127
	v_mul_f32_e32 v128, 0xbfb8aa3b, v128
	v_lshrrev_b32_e32 v156, 8, v156
	v_and_b32_e32 v158, 0xff00, v158
	v_or_b32_e32 v157, v147, v157
	v_exp_f32_e32 v147, v128
	v_mul_f32_e32 v128, 0xbfb8aa3b, v129
	v_or_b32_sdwa v156, v156, v158 dst_sel:DWORD dst_unused:UNUSED_PAD src0_sel:BYTE_0 src1_sel:DWORD
	v_lshlrev_b32_e32 v158, 8, v160
	v_exp_f32_e32 v129, v128
	v_and_b32_e32 v158, 0xff0000, v158
	v_or_b32_e32 v156, v156, v158
	v_lshlrev_b32_e32 v158, 16, v162
	v_add_f32_e32 v127, 1.0, v127
	v_and_b32_e32 v158, 0xff000000, v158
	v_rcp_f32_e32 v128, v127
	v_add_f32_e32 v127, 1.0, v147
	v_mul_f32_e32 v122, 0xbfb8aa3b, v122
	v_mul_f32_e32 v126, 0xbfb8aa3b, v126
	v_or_b32_e32 v156, v156, v158
	v_rcp_f32_e32 v158, v127
	v_add_f32_e32 v127, 1.0, v129
	v_exp_f32_e32 v129, v122
	v_mul_f32_e32 v122, 0xbfb8aa3b, v123
	v_exp_f32_e32 v126, v126
	v_exp_f32_e32 v123, v122
	v_mul_f32_e32 v124, 0xbfb8aa3b, v124
	v_exp_f32_e32 v124, v124
	v_mul_f32_e32 v125, 0xbfb8aa3b, v125
	v_exp_f32_e32 v125, v125
	v_add_f32_e32 v126, 1.0, v126
	v_rcp_f32_e32 v122, v127
	v_add_f32_e32 v127, 1.0, v129
	v_add_f32_e32 v123, 1.0, v123
	v_rcp_f32_e32 v126, v126
	v_rcp_f32_e32 v127, v127
	v_rcp_f32_e32 v129, v123
	v_add_f32_e32 v123, 1.0, v124
	v_rcp_f32_e32 v159, v123
	v_add_f32_e32 v123, 1.0, v125
	v_rcp_f32_e32 v123, v123
	v_pk_fma_f32 v[124:125], v[126:127], s[0:1], v[148:149] op_sel_hi:[1,0,0]
	v_pk_fma_f32 v[126:127], v[128:129], s[0:1], v[148:149] op_sel_hi:[1,0,0]
	v_pk_fma_f32 v[128:129], v[158:159], s[0:1], v[148:149] op_sel_hi:[1,0,0]
	v_lshrrev_b32_e32 v124, 8, v124
	v_and_b32_e32 v126, 0xff00, v126
	v_pk_fma_f32 v[122:123], v[122:123], s[0:1], v[148:149] op_sel_hi:[1,0,0]
	v_lshrrev_b32_e32 v125, 8, v125
	v_and_b32_e32 v127, 0xff00, v127
	v_or_b32_sdwa v124, v124, v126 dst_sel:DWORD dst_unused:UNUSED_PAD src0_sel:BYTE_0 src1_sel:DWORD
	v_lshlrev_b32_e32 v126, 8, v129
	v_or_b32_sdwa v125, v125, v127 dst_sel:DWORD dst_unused:UNUSED_PAD src0_sel:BYTE_0 src1_sel:DWORD
	v_lshlrev_b32_e32 v127, 8, v128
	v_and_b32_e32 v126, 0xff0000, v126
	v_lshlrev_b32_e32 v123, 16, v123
	v_and_b32_e32 v127, 0xff0000, v127
	v_or_b32_e32 v125, v125, v126
	v_lshlrev_b32_e32 v122, 16, v122
	v_and_b32_e32 v123, 0xff000000, v123
	v_or_b32_e32 v124, v124, v127
	v_and_b32_e32 v122, 0xff000000, v122
	v_or_b32_e32 v159, v125, v123
	v_mul_f32_e32 v123, 0xbfb8aa3b, v63
	v_or_b32_e32 v158, v124, v122
	v_exp_f32_e32 v123, v123
	v_mul_f32_e32 v124, 0xbfb8aa3b, v64
	v_exp_f32_e32 v125, v124
	v_mul_f32_e32 v124, 0xbfb8aa3b, v65
	v_exp_f32_e32 v127, v124
	v_add_f32_e32 v123, 1.0, v123
	v_rcp_f32_e32 v124, v123
	v_add_f32_e32 v123, 1.0, v125
	v_rcp_f32_e32 v126, v123
	v_add_f32_e32 v123, 1.0, v127
	v_mul_f32_e32 v125, 0xbfb8aa3b, v58
	v_mul_f32_e32 v127, 0xbfb8aa3b, v59
	v_exp_f32_e32 v125, v125
	v_exp_f32_e32 v127, v127
	v_mul_f32_e32 v122, 0xbfb8aa3b, v62
	v_exp_f32_e32 v122, v122
	v_rcp_f32_e32 v128, v123
	v_add_f32_e32 v123, 1.0, v125
	v_add_f32_e32 v125, 1.0, v127
	v_mul_f32_e32 v127, 0xbfb8aa3b, v60
	v_exp_f32_e32 v127, v127
	v_mul_f32_e32 v129, 0xbfb8aa3b, v61
	v_exp_f32_e32 v129, v129
	v_add_f32_e32 v122, 1.0, v122
	v_rcp_f32_e32 v122, v122
	v_rcp_f32_e32 v123, v123
	v_rcp_f32_e32 v125, v125
	v_add_f32_e32 v127, 1.0, v127
	v_rcp_f32_e32 v127, v127
	v_add_f32_e32 v129, 1.0, v129
	v_rcp_f32_e32 v129, v129
	v_pk_fma_f32 v[122:123], v[122:123], s[0:1], v[148:149] op_sel_hi:[1,0,0]
	v_pk_fma_f32 v[124:125], v[124:125], s[0:1], v[148:149] op_sel_hi:[1,0,0]
	v_pk_fma_f32 v[126:127], v[126:127], s[0:1], v[148:149] op_sel_hi:[1,0,0]
	v_lshrrev_b32_e32 v122, 8, v122
	v_and_b32_e32 v124, 0xff00, v124
	v_lshrrev_b32_e32 v123, 8, v123
	v_and_b32_e32 v125, 0xff00, v125
	v_or_b32_sdwa v122, v122, v124 dst_sel:DWORD dst_unused:UNUSED_PAD src0_sel:BYTE_0 src1_sel:DWORD
	v_lshlrev_b32_e32 v124, 8, v127
	v_pk_fma_f32 v[128:129], v[128:129], s[0:1], v[148:149] op_sel_hi:[1,0,0]
	v_or_b32_sdwa v123, v123, v125 dst_sel:DWORD dst_unused:UNUSED_PAD src0_sel:BYTE_0 src1_sel:DWORD
	v_and_b32_e32 v124, 0xff0000, v124
	v_or_b32_e32 v123, v123, v124
	v_lshlrev_b32_e32 v124, 16, v129
	v_mul_f32_e32 v119, 0xbfb8aa3b, v119
	v_and_b32_e32 v124, 0xff000000, v124
	v_exp_f32_e32 v119, v119
	v_mul_f32_e32 v120, 0xbfb8aa3b, v120
	v_or_b32_e32 v123, v123, v124
	v_exp_f32_e32 v124, v120
	v_mul_f32_e32 v120, 0xbfb8aa3b, v121
	v_exp_f32_e32 v121, v120
	v_add_f32_e32 v119, 1.0, v119
	v_rcp_f32_e32 v120, v119
	v_add_f32_e32 v119, 1.0, v124
	v_mul_f32_e32 v114, 0xbfb8aa3b, v114
	v_mul_f32_e32 v118, 0xbfb8aa3b, v118
	v_rcp_f32_e32 v124, v119
	v_add_f32_e32 v119, 1.0, v121
	v_exp_f32_e32 v121, v114
	v_mul_f32_e32 v114, 0xbfb8aa3b, v115
	v_exp_f32_e32 v118, v118
	v_exp_f32_e32 v115, v114
	v_mul_f32_e32 v116, 0xbfb8aa3b, v116
	v_exp_f32_e32 v116, v116
	v_mul_f32_e32 v117, 0xbfb8aa3b, v117
	v_lshlrev_b32_e32 v125, 8, v126
	v_exp_f32_e32 v117, v117
	v_and_b32_e32 v125, 0xff0000, v125
	v_or_b32_e32 v122, v122, v125
	v_lshlrev_b32_e32 v125, 16, v128
	v_add_f32_e32 v118, 1.0, v118
	v_rcp_f32_e32 v114, v119
	v_add_f32_e32 v119, 1.0, v121
	v_add_f32_e32 v115, 1.0, v115
	v_and_b32_e32 v125, 0xff000000, v125
	v_rcp_f32_e32 v118, v118
	v_rcp_f32_e32 v119, v119
	v_rcp_f32_e32 v121, v115
	v_add_f32_e32 v115, 1.0, v116
	v_or_b32_e32 v122, v122, v125
	v_rcp_f32_e32 v125, v115
	v_add_f32_e32 v115, 1.0, v117
	v_rcp_f32_e32 v115, v115
	v_pk_fma_f32 v[116:117], v[118:119], s[0:1], v[148:149] op_sel_hi:[1,0,0]
	v_pk_fma_f32 v[118:119], v[120:121], s[0:1], v[148:149] op_sel_hi:[1,0,0]
	v_pk_fma_f32 v[120:121], v[124:125], s[0:1], v[148:149] op_sel_hi:[1,0,0]
	v_lshrrev_b32_e32 v116, 8, v116
	v_and_b32_e32 v118, 0xff00, v118
	v_pk_fma_f32 v[114:115], v[114:115], s[0:1], v[148:149] op_sel_hi:[1,0,0]
	v_lshrrev_b32_e32 v117, 8, v117
	v_and_b32_e32 v119, 0xff00, v119
	v_or_b32_sdwa v116, v116, v118 dst_sel:DWORD dst_unused:UNUSED_PAD src0_sel:BYTE_0 src1_sel:DWORD
	v_lshlrev_b32_e32 v118, 8, v121
	v_or_b32_sdwa v117, v117, v119 dst_sel:DWORD dst_unused:UNUSED_PAD src0_sel:BYTE_0 src1_sel:DWORD
	v_lshlrev_b32_e32 v119, 8, v120
	v_and_b32_e32 v118, 0xff0000, v118
	v_lshlrev_b32_e32 v115, 16, v115
	v_and_b32_e32 v119, 0xff0000, v119
	v_or_b32_e32 v117, v117, v118
	v_lshlrev_b32_e32 v114, 16, v114
	v_and_b32_e32 v115, 0xff000000, v115
	v_or_b32_e32 v116, v116, v119
	v_and_b32_e32 v114, 0xff000000, v114
	v_or_b32_e32 v125, v117, v115
	v_mul_f32_e32 v115, 0xbfb8aa3b, v51
	v_or_b32_e32 v124, v116, v114
	v_exp_f32_e32 v115, v115
	v_mul_f32_e32 v116, 0xbfb8aa3b, v52
	v_exp_f32_e32 v117, v116
	v_mul_f32_e32 v116, 0xbfb8aa3b, v53
	v_exp_f32_e32 v119, v116
	v_add_f32_e32 v115, 1.0, v115
	v_rcp_f32_e32 v116, v115
	v_add_f32_e32 v115, 1.0, v117
	v_rcp_f32_e32 v118, v115
	v_add_f32_e32 v115, 1.0, v119
	v_mul_f32_e32 v117, 0xbfb8aa3b, v46
	v_mul_f32_e32 v119, 0xbfb8aa3b, v47
	v_exp_f32_e32 v117, v117
	v_exp_f32_e32 v119, v119
	v_mul_f32_e32 v114, 0xbfb8aa3b, v50
	v_exp_f32_e32 v114, v114
	v_rcp_f32_e32 v120, v115
	v_add_f32_e32 v115, 1.0, v117
	v_add_f32_e32 v117, 1.0, v119
	v_mul_f32_e32 v119, 0xbfb8aa3b, v48
	v_exp_f32_e32 v119, v119
	v_mul_f32_e32 v121, 0xbfb8aa3b, v49
	v_exp_f32_e32 v121, v121
	v_add_f32_e32 v114, 1.0, v114
	v_rcp_f32_e32 v114, v114
	v_rcp_f32_e32 v115, v115
	v_rcp_f32_e32 v117, v117
	v_add_f32_e32 v119, 1.0, v119
	v_rcp_f32_e32 v119, v119
	v_add_f32_e32 v121, 1.0, v121
	v_rcp_f32_e32 v121, v121
	v_pk_fma_f32 v[114:115], v[114:115], s[0:1], v[148:149] op_sel_hi:[1,0,0]
	v_pk_fma_f32 v[116:117], v[116:117], s[0:1], v[148:149] op_sel_hi:[1,0,0]
	v_pk_fma_f32 v[118:119], v[118:119], s[0:1], v[148:149] op_sel_hi:[1,0,0]
	v_lshrrev_b32_e32 v114, 8, v114
	v_and_b32_e32 v116, 0xff00, v116
	v_lshrrev_b32_e32 v115, 8, v115
	v_and_b32_e32 v117, 0xff00, v117
	v_or_b32_sdwa v114, v114, v116 dst_sel:DWORD dst_unused:UNUSED_PAD src0_sel:BYTE_0 src1_sel:DWORD
	v_lshlrev_b32_e32 v116, 8, v119
	v_pk_fma_f32 v[120:121], v[120:121], s[0:1], v[148:149] op_sel_hi:[1,0,0]
	v_or_b32_sdwa v115, v115, v117 dst_sel:DWORD dst_unused:UNUSED_PAD src0_sel:BYTE_0 src1_sel:DWORD
	v_and_b32_e32 v116, 0xff0000, v116
	v_or_b32_e32 v115, v115, v116
	v_lshlrev_b32_e32 v116, 16, v121
	v_mul_f32_e32 v111, 0xbfb8aa3b, v111
	v_and_b32_e32 v116, 0xff000000, v116
	v_exp_f32_e32 v111, v111
	v_mul_f32_e32 v112, 0xbfb8aa3b, v112
	v_or_b32_e32 v115, v115, v116
	v_exp_f32_e32 v116, v112
	v_mul_f32_e32 v112, 0xbfb8aa3b, v113
	v_exp_f32_e32 v113, v112
	v_add_f32_e32 v111, 1.0, v111
	v_rcp_f32_e32 v112, v111
	v_add_f32_e32 v111, 1.0, v116
	v_mul_f32_e32 v106, 0xbfb8aa3b, v106
	v_mul_f32_e32 v110, 0xbfb8aa3b, v110
	v_rcp_f32_e32 v116, v111
	v_add_f32_e32 v111, 1.0, v113
	v_exp_f32_e32 v113, v106
	v_mul_f32_e32 v106, 0xbfb8aa3b, v107
	v_exp_f32_e32 v110, v110
	v_exp_f32_e32 v107, v106
	v_mul_f32_e32 v108, 0xbfb8aa3b, v108
	v_exp_f32_e32 v108, v108
	v_mul_f32_e32 v109, 0xbfb8aa3b, v109
	v_lshlrev_b32_e32 v117, 8, v118
	v_exp_f32_e32 v109, v109
	v_and_b32_e32 v117, 0xff0000, v117
	v_or_b32_e32 v114, v114, v117
	v_lshlrev_b32_e32 v117, 16, v120
	v_add_f32_e32 v110, 1.0, v110
	v_rcp_f32_e32 v106, v111
	v_add_f32_e32 v111, 1.0, v113
	v_add_f32_e32 v107, 1.0, v107
	v_and_b32_e32 v117, 0xff000000, v117
	v_rcp_f32_e32 v110, v110
	v_rcp_f32_e32 v111, v111
	v_rcp_f32_e32 v113, v107
	v_add_f32_e32 v107, 1.0, v108
	v_or_b32_e32 v114, v114, v117
	v_rcp_f32_e32 v117, v107
	v_add_f32_e32 v107, 1.0, v109
	v_rcp_f32_e32 v107, v107
	v_pk_fma_f32 v[108:109], v[110:111], s[0:1], v[148:149] op_sel_hi:[1,0,0]
	v_pk_fma_f32 v[110:111], v[112:113], s[0:1], v[148:149] op_sel_hi:[1,0,0]
	v_pk_fma_f32 v[112:113], v[116:117], s[0:1], v[148:149] op_sel_hi:[1,0,0]
	v_lshrrev_b32_e32 v108, 8, v108
	v_and_b32_e32 v110, 0xff00, v110
	v_pk_fma_f32 v[106:107], v[106:107], s[0:1], v[148:149] op_sel_hi:[1,0,0]
	v_lshrrev_b32_e32 v109, 8, v109
	v_and_b32_e32 v111, 0xff00, v111
	v_or_b32_sdwa v108, v108, v110 dst_sel:DWORD dst_unused:UNUSED_PAD src0_sel:BYTE_0 src1_sel:DWORD
	v_lshlrev_b32_e32 v110, 8, v113
	v_or_b32_sdwa v109, v109, v111 dst_sel:DWORD dst_unused:UNUSED_PAD src0_sel:BYTE_0 src1_sel:DWORD
	v_lshlrev_b32_e32 v111, 8, v112
	v_and_b32_e32 v110, 0xff0000, v110
	v_lshlrev_b32_e32 v107, 16, v107
	v_and_b32_e32 v111, 0xff0000, v111
	v_or_b32_e32 v109, v109, v110
	v_lshlrev_b32_e32 v106, 16, v106
	v_and_b32_e32 v107, 0xff000000, v107
	v_or_b32_e32 v108, v108, v111
	v_and_b32_e32 v106, 0xff000000, v106
	v_or_b32_e32 v117, v109, v107
	v_mul_f32_e32 v107, 0xbfb8aa3b, v43
	v_or_b32_e32 v116, v108, v106
	v_exp_f32_e32 v107, v107
	v_mul_f32_e32 v108, 0xbfb8aa3b, v44
	v_exp_f32_e32 v109, v108
	v_mul_f32_e32 v108, 0xbfb8aa3b, v45
	v_exp_f32_e32 v111, v108
	v_add_f32_e32 v107, 1.0, v107
	v_rcp_f32_e32 v108, v107
	v_add_f32_e32 v107, 1.0, v109
	v_rcp_f32_e32 v110, v107
	v_add_f32_e32 v107, 1.0, v111
	v_mul_f32_e32 v109, 0xbfb8aa3b, v38
	v_mul_f32_e32 v111, 0xbfb8aa3b, v39
	v_exp_f32_e32 v109, v109
	v_exp_f32_e32 v111, v111
	v_mul_f32_e32 v106, 0xbfb8aa3b, v42
	v_exp_f32_e32 v106, v106
	v_rcp_f32_e32 v112, v107
	v_add_f32_e32 v107, 1.0, v109
	v_add_f32_e32 v109, 1.0, v111
	v_mul_f32_e32 v111, 0xbfb8aa3b, v40
	v_exp_f32_e32 v111, v111
	v_mul_f32_e32 v113, 0xbfb8aa3b, v41
	v_exp_f32_e32 v113, v113
	v_add_f32_e32 v106, 1.0, v106
	v_rcp_f32_e32 v106, v106
	v_rcp_f32_e32 v107, v107
	v_rcp_f32_e32 v109, v109
	v_add_f32_e32 v111, 1.0, v111
	v_rcp_f32_e32 v111, v111
	v_add_f32_e32 v113, 1.0, v113
	v_rcp_f32_e32 v113, v113
	v_pk_fma_f32 v[106:107], v[106:107], s[0:1], v[148:149] op_sel_hi:[1,0,0]
	v_pk_fma_f32 v[108:109], v[108:109], s[0:1], v[148:149] op_sel_hi:[1,0,0]
	v_pk_fma_f32 v[110:111], v[110:111], s[0:1], v[148:149] op_sel_hi:[1,0,0]
	v_lshrrev_b32_e32 v106, 8, v106
	v_and_b32_e32 v108, 0xff00, v108
	v_lshrrev_b32_e32 v107, 8, v107
	v_and_b32_e32 v109, 0xff00, v109
	v_or_b32_sdwa v106, v106, v108 dst_sel:DWORD dst_unused:UNUSED_PAD src0_sel:BYTE_0 src1_sel:DWORD
	v_lshlrev_b32_e32 v108, 8, v111
	v_pk_fma_f32 v[112:113], v[112:113], s[0:1], v[148:149] op_sel_hi:[1,0,0]
	v_or_b32_sdwa v107, v107, v109 dst_sel:DWORD dst_unused:UNUSED_PAD src0_sel:BYTE_0 src1_sel:DWORD
	v_and_b32_e32 v108, 0xff0000, v108
	v_or_b32_e32 v107, v107, v108
	v_lshlrev_b32_e32 v108, 16, v113
	v_mul_f32_e32 v103, 0xbfb8aa3b, v103
	v_and_b32_e32 v108, 0xff000000, v108
	v_exp_f32_e32 v103, v103
	v_mul_f32_e32 v104, 0xbfb8aa3b, v104
	v_or_b32_e32 v107, v107, v108
	v_exp_f32_e32 v108, v104
	v_mul_f32_e32 v104, 0xbfb8aa3b, v105
	v_exp_f32_e32 v105, v104
	v_add_f32_e32 v103, 1.0, v103
	v_rcp_f32_e32 v104, v103
	v_add_f32_e32 v103, 1.0, v108
	v_mul_f32_e32 v98, 0xbfb8aa3b, v98
	v_mul_f32_e32 v102, 0xbfb8aa3b, v102
	v_rcp_f32_e32 v108, v103
	v_add_f32_e32 v103, 1.0, v105
	v_exp_f32_e32 v105, v98
	v_mul_f32_e32 v98, 0xbfb8aa3b, v99
	v_exp_f32_e32 v102, v102
	v_exp_f32_e32 v99, v98
	v_mul_f32_e32 v100, 0xbfb8aa3b, v100
	v_exp_f32_e32 v100, v100
	v_mul_f32_e32 v101, 0xbfb8aa3b, v101
	v_lshlrev_b32_e32 v109, 8, v110
	v_exp_f32_e32 v101, v101
	v_and_b32_e32 v109, 0xff0000, v109
	v_or_b32_e32 v106, v106, v109
	v_lshlrev_b32_e32 v109, 16, v112
	v_add_f32_e32 v102, 1.0, v102
	v_rcp_f32_e32 v98, v103
	v_add_f32_e32 v103, 1.0, v105
	v_add_f32_e32 v99, 1.0, v99
	v_and_b32_e32 v109, 0xff000000, v109
	v_rcp_f32_e32 v102, v102
	v_rcp_f32_e32 v103, v103
	v_rcp_f32_e32 v105, v99
	v_add_f32_e32 v99, 1.0, v100
	v_or_b32_e32 v106, v106, v109
	v_rcp_f32_e32 v109, v99
	v_add_f32_e32 v99, 1.0, v101
	v_rcp_f32_e32 v99, v99
	v_pk_fma_f32 v[100:101], v[102:103], s[0:1], v[148:149] op_sel_hi:[1,0,0]
	v_pk_fma_f32 v[102:103], v[104:105], s[0:1], v[148:149] op_sel_hi:[1,0,0]
	v_pk_fma_f32 v[104:105], v[108:109], s[0:1], v[148:149] op_sel_hi:[1,0,0]
	v_lshrrev_b32_e32 v100, 8, v100
	v_and_b32_e32 v102, 0xff00, v102
	v_pk_fma_f32 v[98:99], v[98:99], s[0:1], v[148:149] op_sel_hi:[1,0,0]
	v_lshrrev_b32_e32 v101, 8, v101
	v_and_b32_e32 v103, 0xff00, v103
	v_or_b32_sdwa v100, v100, v102 dst_sel:DWORD dst_unused:UNUSED_PAD src0_sel:BYTE_0 src1_sel:DWORD
	v_lshlrev_b32_e32 v102, 8, v105
	v_or_b32_sdwa v101, v101, v103 dst_sel:DWORD dst_unused:UNUSED_PAD src0_sel:BYTE_0 src1_sel:DWORD
	v_lshlrev_b32_e32 v103, 8, v104
	v_and_b32_e32 v102, 0xff0000, v102
	v_lshlrev_b32_e32 v99, 16, v99
	v_and_b32_e32 v103, 0xff0000, v103
	v_or_b32_e32 v101, v101, v102
	v_lshlrev_b32_e32 v98, 16, v98
	v_and_b32_e32 v99, 0xff000000, v99
	v_or_b32_e32 v100, v100, v103
	v_and_b32_e32 v98, 0xff000000, v98
	v_or_b32_e32 v109, v101, v99
	v_mul_f32_e32 v99, 0xbfb8aa3b, v31
	v_or_b32_e32 v108, v100, v98
	v_exp_f32_e32 v99, v99
	v_mul_f32_e32 v100, 0xbfb8aa3b, v32
	v_exp_f32_e32 v101, v100
	v_mul_f32_e32 v100, 0xbfb8aa3b, v33
	v_exp_f32_e32 v103, v100
	v_add_f32_e32 v99, 1.0, v99
	v_rcp_f32_e32 v100, v99
	v_add_f32_e32 v99, 1.0, v101
	v_rcp_f32_e32 v102, v99
	v_add_f32_e32 v99, 1.0, v103
	v_mul_f32_e32 v101, 0xbfb8aa3b, v26
	v_mul_f32_e32 v103, 0xbfb8aa3b, v27
	v_exp_f32_e32 v101, v101
	v_exp_f32_e32 v103, v103
	v_mul_f32_e32 v98, 0xbfb8aa3b, v30
	v_exp_f32_e32 v98, v98
	v_rcp_f32_e32 v104, v99
	v_add_f32_e32 v99, 1.0, v101
	v_add_f32_e32 v101, 1.0, v103
	v_mul_f32_e32 v103, 0xbfb8aa3b, v28
	v_exp_f32_e32 v103, v103
	v_mul_f32_e32 v105, 0xbfb8aa3b, v29
	v_exp_f32_e32 v105, v105
	v_add_f32_e32 v98, 1.0, v98
	v_rcp_f32_e32 v98, v98
	v_rcp_f32_e32 v99, v99
	v_rcp_f32_e32 v101, v101
	v_add_f32_e32 v103, 1.0, v103
	v_rcp_f32_e32 v103, v103
	v_add_f32_e32 v105, 1.0, v105
	v_rcp_f32_e32 v105, v105
	v_pk_fma_f32 v[98:99], v[98:99], s[0:1], v[148:149] op_sel_hi:[1,0,0]
	v_pk_fma_f32 v[100:101], v[100:101], s[0:1], v[148:149] op_sel_hi:[1,0,0]
	v_pk_fma_f32 v[102:103], v[102:103], s[0:1], v[148:149] op_sel_hi:[1,0,0]
	v_lshrrev_b32_e32 v98, 8, v98
	v_and_b32_e32 v100, 0xff00, v100
	v_lshrrev_b32_e32 v99, 8, v99
	v_and_b32_e32 v101, 0xff00, v101
	v_or_b32_sdwa v98, v98, v100 dst_sel:DWORD dst_unused:UNUSED_PAD src0_sel:BYTE_0 src1_sel:DWORD
	v_lshlrev_b32_e32 v100, 8, v103
	v_pk_fma_f32 v[104:105], v[104:105], s[0:1], v[148:149] op_sel_hi:[1,0,0]
	v_or_b32_sdwa v99, v99, v101 dst_sel:DWORD dst_unused:UNUSED_PAD src0_sel:BYTE_0 src1_sel:DWORD
	v_and_b32_e32 v100, 0xff0000, v100
	v_or_b32_e32 v99, v99, v100
	v_lshlrev_b32_e32 v100, 16, v105
	v_mul_f32_e32 v95, 0xbfb8aa3b, v95
	v_and_b32_e32 v100, 0xff000000, v100
	v_exp_f32_e32 v95, v95
	v_mul_f32_e32 v96, 0xbfb8aa3b, v96
	v_or_b32_e32 v99, v99, v100
	v_exp_f32_e32 v100, v96
	v_mul_f32_e32 v96, 0xbfb8aa3b, v97
	v_exp_f32_e32 v97, v96
	v_add_f32_e32 v95, 1.0, v95
	v_rcp_f32_e32 v96, v95
	v_add_f32_e32 v95, 1.0, v100
	v_mul_f32_e32 v90, 0xbfb8aa3b, v90
	v_mul_f32_e32 v94, 0xbfb8aa3b, v94
	v_rcp_f32_e32 v100, v95
	v_add_f32_e32 v95, 1.0, v97
	v_exp_f32_e32 v97, v90
	v_mul_f32_e32 v90, 0xbfb8aa3b, v91
	v_exp_f32_e32 v94, v94
	v_exp_f32_e32 v91, v90
	v_mul_f32_e32 v92, 0xbfb8aa3b, v92
	v_exp_f32_e32 v92, v92
	v_mul_f32_e32 v93, 0xbfb8aa3b, v93
	v_lshlrev_b32_e32 v101, 8, v102
	v_exp_f32_e32 v93, v93
	v_and_b32_e32 v101, 0xff0000, v101
	v_or_b32_e32 v98, v98, v101
	v_lshlrev_b32_e32 v101, 16, v104
	v_add_f32_e32 v94, 1.0, v94
	v_rcp_f32_e32 v90, v95
	v_add_f32_e32 v95, 1.0, v97
	v_add_f32_e32 v91, 1.0, v91
	v_and_b32_e32 v101, 0xff000000, v101
	v_rcp_f32_e32 v94, v94
	v_rcp_f32_e32 v95, v95
	v_rcp_f32_e32 v97, v91
	v_add_f32_e32 v91, 1.0, v92
	v_or_b32_e32 v98, v98, v101
	v_rcp_f32_e32 v101, v91
	v_add_f32_e32 v91, 1.0, v93
	v_rcp_f32_e32 v91, v91
	v_pk_fma_f32 v[92:93], v[94:95], s[0:1], v[148:149] op_sel_hi:[1,0,0]
	v_pk_fma_f32 v[94:95], v[96:97], s[0:1], v[148:149] op_sel_hi:[1,0,0]
	v_pk_fma_f32 v[96:97], v[100:101], s[0:1], v[148:149] op_sel_hi:[1,0,0]
	v_lshrrev_b32_e32 v92, 8, v92
	v_and_b32_e32 v94, 0xff00, v94
	v_pk_fma_f32 v[90:91], v[90:91], s[0:1], v[148:149] op_sel_hi:[1,0,0]
	v_lshrrev_b32_e32 v93, 8, v93
	v_and_b32_e32 v95, 0xff00, v95
	v_or_b32_sdwa v92, v92, v94 dst_sel:DWORD dst_unused:UNUSED_PAD src0_sel:BYTE_0 src1_sel:DWORD
	v_lshlrev_b32_e32 v94, 8, v97
	v_or_b32_sdwa v93, v93, v95 dst_sel:DWORD dst_unused:UNUSED_PAD src0_sel:BYTE_0 src1_sel:DWORD
	v_and_b32_e32 v94, 0xff0000, v94
	v_lshlrev_b32_e32 v91, 16, v91
	v_or_b32_e32 v93, v93, v94
	v_and_b32_e32 v91, 0xff000000, v91
	v_lshlrev_b32_e32 v95, 8, v96
	v_or_b32_e32 v101, v93, v91
	v_mul_f32_e32 v93, 0xbfb8aa3b, v23
	v_and_b32_e32 v95, 0xff0000, v95
	v_exp_f32_e32 v93, v93
	v_mul_f32_e32 v94, 0xbfb8aa3b, v24
	v_or_b32_e32 v92, v92, v95
	v_exp_f32_e32 v95, v94
	v_mul_f32_e32 v94, 0xbfb8aa3b, v25
	v_exp_f32_e32 v97, v94
	v_add_f32_e32 v93, 1.0, v93
	v_rcp_f32_e32 v94, v93
	v_add_f32_e32 v93, 1.0, v95
	v_rcp_f32_e32 v96, v93
	v_add_f32_e32 v93, 1.0, v97
	v_mul_f32_e32 v95, 0xbfb8aa3b, v18
	v_mul_f32_e32 v97, 0xbfb8aa3b, v19
	v_lshlrev_b32_e32 v90, 16, v90
	v_exp_f32_e32 v95, v95
	v_exp_f32_e32 v97, v97
	v_and_b32_e32 v90, 0xff000000, v90
	v_or_b32_e32 v100, v92, v90
	v_add_co_u32_e32 v90, vcc, s27, v150
	v_mul_f32_e32 v92, 0xbfb8aa3b, v22
	s_nop 0
	v_addc_co_u32_e32 v91, vcc, 0, v151, vcc
	v_exp_f32_e32 v92, v92
	global_store_dwordx4 v[90:91], v[98:101], off sc1 nt
	v_mul_f32_e32 v87, 0xbfb8aa3b, v87
	v_exp_f32_e32 v87, v87
	v_rcp_f32_e32 v98, v93
	v_add_f32_e32 v93, 1.0, v95
	v_add_f32_e32 v95, 1.0, v97
	v_mul_f32_e32 v97, 0xbfb8aa3b, v20
	v_exp_f32_e32 v97, v97
	v_mul_f32_e32 v99, 0xbfb8aa3b, v21
	v_exp_f32_e32 v99, v99
	v_add_f32_e32 v92, 1.0, v92
	v_rcp_f32_e32 v92, v92
	v_rcp_f32_e32 v93, v93
	v_rcp_f32_e32 v95, v95
	v_add_f32_e32 v97, 1.0, v97
	v_rcp_f32_e32 v97, v97
	v_add_f32_e32 v99, 1.0, v99
	v_rcp_f32_e32 v99, v99
	v_pk_fma_f32 v[92:93], v[92:93], s[0:1], v[148:149] op_sel_hi:[1,0,0]
	v_pk_fma_f32 v[94:95], v[94:95], s[0:1], v[148:149] op_sel_hi:[1,0,0]
	v_pk_fma_f32 v[96:97], v[96:97], s[0:1], v[148:149] op_sel_hi:[1,0,0]
	v_lshrrev_b32_e32 v92, 8, v92
	v_and_b32_e32 v94, 0xff00, v94
	v_lshrrev_b32_e32 v93, 8, v93
	v_and_b32_e32 v95, 0xff00, v95
	v_or_b32_sdwa v92, v92, v94 dst_sel:DWORD dst_unused:UNUSED_PAD src0_sel:BYTE_0 src1_sel:DWORD
	v_lshlrev_b32_e32 v94, 8, v97
	v_pk_fma_f32 v[98:99], v[98:99], s[0:1], v[148:149] op_sel_hi:[1,0,0]
	v_or_b32_sdwa v93, v93, v95 dst_sel:DWORD dst_unused:UNUSED_PAD src0_sel:BYTE_0 src1_sel:DWORD
	v_and_b32_e32 v94, 0xff0000, v94
	v_or_b32_e32 v93, v93, v94
	v_lshlrev_b32_e32 v94, 16, v99
	v_and_b32_e32 v94, 0xff000000, v94
	v_mul_f32_e32 v88, 0xbfb8aa3b, v88
	v_or_b32_e32 v93, v93, v94
	v_exp_f32_e32 v94, v88
	v_mul_f32_e32 v88, 0xbfb8aa3b, v89
	v_exp_f32_e32 v89, v88
	v_add_f32_e32 v87, 1.0, v87
	v_rcp_f32_e32 v88, v87
	v_add_f32_e32 v87, 1.0, v94
	v_mul_f32_e32 v82, 0xbfb8aa3b, v82
	v_mul_f32_e32 v86, 0xbfb8aa3b, v86
	v_rcp_f32_e32 v94, v87
	v_add_f32_e32 v87, 1.0, v89
	v_exp_f32_e32 v89, v82
	v_mul_f32_e32 v82, 0xbfb8aa3b, v83
	v_exp_f32_e32 v86, v86
	v_exp_f32_e32 v83, v82
	v_mul_f32_e32 v84, 0xbfb8aa3b, v84
	v_exp_f32_e32 v84, v84
	v_mul_f32_e32 v85, 0xbfb8aa3b, v85
	v_lshlrev_b32_e32 v95, 8, v96
	v_exp_f32_e32 v85, v85
	v_and_b32_e32 v95, 0xff0000, v95
	v_or_b32_e32 v92, v92, v95
	v_lshlrev_b32_e32 v95, 16, v98
	v_add_f32_e32 v86, 1.0, v86
	v_rcp_f32_e32 v82, v87
	v_add_f32_e32 v87, 1.0, v89
	v_add_f32_e32 v83, 1.0, v83
	v_and_b32_e32 v95, 0xff000000, v95
	v_rcp_f32_e32 v86, v86
	v_rcp_f32_e32 v87, v87
	v_rcp_f32_e32 v89, v83
	v_add_f32_e32 v83, 1.0, v84
	v_or_b32_e32 v92, v92, v95
	v_rcp_f32_e32 v95, v83
	v_add_f32_e32 v83, 1.0, v85
	v_rcp_f32_e32 v83, v83
	v_pk_fma_f32 v[84:85], v[86:87], s[0:1], v[148:149] op_sel_hi:[1,0,0]
	v_pk_fma_f32 v[86:87], v[88:89], s[0:1], v[148:149] op_sel_hi:[1,0,0]
	v_pk_fma_f32 v[88:89], v[94:95], s[0:1], v[148:149] op_sel_hi:[1,0,0]
	v_lshrrev_b32_e32 v84, 8, v84
	v_and_b32_e32 v86, 0xff00, v86
	v_pk_fma_f32 v[82:83], v[82:83], s[0:1], v[148:149] op_sel_hi:[1,0,0]
	v_lshrrev_b32_e32 v85, 8, v85
	v_and_b32_e32 v87, 0xff00, v87
	v_or_b32_sdwa v84, v84, v86 dst_sel:DWORD dst_unused:UNUSED_PAD src0_sel:BYTE_0 src1_sel:DWORD
	v_lshlrev_b32_e32 v86, 8, v89
	v_or_b32_sdwa v85, v85, v87 dst_sel:DWORD dst_unused:UNUSED_PAD src0_sel:BYTE_0 src1_sel:DWORD
	v_lshlrev_b32_e32 v87, 8, v88
	v_and_b32_e32 v86, 0xff0000, v86
	v_lshlrev_b32_e32 v83, 16, v83
	v_and_b32_e32 v87, 0xff0000, v87
	v_or_b32_e32 v85, v85, v86
	v_lshlrev_b32_e32 v82, 16, v82
	v_and_b32_e32 v83, 0xff000000, v83
	v_or_b32_e32 v84, v84, v87
	v_and_b32_e32 v82, 0xff000000, v82
	v_or_b32_e32 v95, v85, v83
	v_mul_f32_e32 v83, 0xbfb8aa3b, v15
	v_or_b32_e32 v94, v84, v82
	v_exp_f32_e32 v83, v83
	v_mul_f32_e32 v84, 0xbfb8aa3b, v16
	v_exp_f32_e32 v85, v84
	v_mul_f32_e32 v84, 0xbfb8aa3b, v17
	v_exp_f32_e32 v87, v84
	v_add_f32_e32 v83, 1.0, v83
	v_rcp_f32_e32 v84, v83
	v_add_f32_e32 v83, 1.0, v85
	v_rcp_f32_e32 v86, v83
	v_add_f32_e32 v83, 1.0, v87
	v_mul_f32_e32 v85, 0xbfb8aa3b, v10
	v_mul_f32_e32 v87, 0xbfb8aa3b, v11
	v_exp_f32_e32 v85, v85
	v_exp_f32_e32 v87, v87
	v_mul_f32_e32 v82, 0xbfb8aa3b, v14
	v_exp_f32_e32 v82, v82
	v_rcp_f32_e32 v88, v83
	v_add_f32_e32 v83, 1.0, v85
	v_add_f32_e32 v85, 1.0, v87
	v_mul_f32_e32 v87, 0xbfb8aa3b, v12
	v_exp_f32_e32 v87, v87
	v_mul_f32_e32 v89, 0xbfb8aa3b, v13
	v_exp_f32_e32 v89, v89
	v_add_f32_e32 v82, 1.0, v82
	v_rcp_f32_e32 v82, v82
	v_rcp_f32_e32 v83, v83
	v_rcp_f32_e32 v85, v85
	v_add_f32_e32 v87, 1.0, v87
	v_rcp_f32_e32 v87, v87
	v_add_f32_e32 v89, 1.0, v89
	v_rcp_f32_e32 v89, v89
	v_pk_fma_f32 v[82:83], v[82:83], s[0:1], v[148:149] op_sel_hi:[1,0,0]
	v_pk_fma_f32 v[84:85], v[84:85], s[0:1], v[148:149] op_sel_hi:[1,0,0]
	v_pk_fma_f32 v[86:87], v[86:87], s[0:1], v[148:149] op_sel_hi:[1,0,0]
	v_lshrrev_b32_e32 v82, 8, v82
	v_and_b32_e32 v84, 0xff00, v84
	v_lshrrev_b32_e32 v83, 8, v83
	v_and_b32_e32 v85, 0xff00, v85
	v_or_b32_sdwa v82, v82, v84 dst_sel:DWORD dst_unused:UNUSED_PAD src0_sel:BYTE_0 src1_sel:DWORD
	v_lshlrev_b32_e32 v84, 8, v87
	v_pk_fma_f32 v[88:89], v[88:89], s[0:1], v[148:149] op_sel_hi:[1,0,0]
	v_or_b32_sdwa v83, v83, v85 dst_sel:DWORD dst_unused:UNUSED_PAD src0_sel:BYTE_0 src1_sel:DWORD
	v_and_b32_e32 v84, 0xff0000, v84
	v_or_b32_e32 v83, v83, v84
	v_lshlrev_b32_e32 v84, 16, v89
	v_mul_f32_e32 v79, 0xbfb8aa3b, v79
	v_and_b32_e32 v84, 0xff000000, v84
	v_exp_f32_e32 v79, v79
	v_mul_f32_e32 v80, 0xbfb8aa3b, v80
	v_or_b32_e32 v83, v83, v84
	v_exp_f32_e32 v84, v80
	v_mul_f32_e32 v80, 0xbfb8aa3b, v81
	v_exp_f32_e32 v81, v80
	v_add_f32_e32 v79, 1.0, v79
	v_rcp_f32_e32 v80, v79
	v_add_f32_e32 v79, 1.0, v84
	v_mul_f32_e32 v74, 0xbfb8aa3b, v74
	v_mul_f32_e32 v78, 0xbfb8aa3b, v78
	v_rcp_f32_e32 v84, v79
	v_add_f32_e32 v79, 1.0, v81
	v_exp_f32_e32 v81, v74
	v_mul_f32_e32 v74, 0xbfb8aa3b, v75
	v_exp_f32_e32 v78, v78
	v_exp_f32_e32 v75, v74
	v_mul_f32_e32 v76, 0xbfb8aa3b, v76
	v_exp_f32_e32 v76, v76
	v_mul_f32_e32 v77, 0xbfb8aa3b, v77
	v_lshlrev_b32_e32 v85, 8, v86
	v_exp_f32_e32 v77, v77
	v_and_b32_e32 v85, 0xff0000, v85
	v_or_b32_e32 v82, v82, v85
	v_lshlrev_b32_e32 v85, 16, v88
	v_add_f32_e32 v78, 1.0, v78
	v_rcp_f32_e32 v74, v79
	v_add_f32_e32 v79, 1.0, v81
	v_add_f32_e32 v75, 1.0, v75
	v_and_b32_e32 v85, 0xff000000, v85
	v_rcp_f32_e32 v78, v78
	v_rcp_f32_e32 v79, v79
	v_rcp_f32_e32 v81, v75
	v_add_f32_e32 v75, 1.0, v76
	v_or_b32_e32 v82, v82, v85
	v_rcp_f32_e32 v85, v75
	v_add_f32_e32 v75, 1.0, v77
	v_rcp_f32_e32 v75, v75
	v_pk_fma_f32 v[76:77], v[78:79], s[0:1], v[148:149] op_sel_hi:[1,0,0]
	v_pk_fma_f32 v[78:79], v[80:81], s[0:1], v[148:149] op_sel_hi:[1,0,0]
	v_pk_fma_f32 v[80:81], v[84:85], s[0:1], v[148:149] op_sel_hi:[1,0,0]
	v_lshrrev_b32_e32 v76, 8, v76
	v_and_b32_e32 v78, 0xff00, v78
	v_pk_fma_f32 v[74:75], v[74:75], s[0:1], v[148:149] op_sel_hi:[1,0,0]
	v_lshrrev_b32_e32 v77, 8, v77
	v_and_b32_e32 v79, 0xff00, v79
	v_or_b32_sdwa v76, v76, v78 dst_sel:DWORD dst_unused:UNUSED_PAD src0_sel:BYTE_0 src1_sel:DWORD
	v_lshlrev_b32_e32 v78, 8, v81
	v_or_b32_sdwa v77, v77, v79 dst_sel:DWORD dst_unused:UNUSED_PAD src0_sel:BYTE_0 src1_sel:DWORD
	v_lshlrev_b32_e32 v79, 8, v80
	v_and_b32_e32 v78, 0xff0000, v78
	v_lshlrev_b32_e32 v75, 16, v75
	v_and_b32_e32 v79, 0xff0000, v79
	v_or_b32_e32 v77, v77, v78
	v_lshlrev_b32_e32 v74, 16, v74
	v_and_b32_e32 v75, 0xff000000, v75
	v_or_b32_e32 v76, v76, v79
	v_and_b32_e32 v74, 0xff000000, v74
	v_or_b32_e32 v85, v77, v75
	v_mul_f32_e32 v75, 0xbfb8aa3b, v7
	v_or_b32_e32 v84, v76, v74
	v_exp_f32_e32 v75, v75
	v_mul_f32_e32 v76, 0xbfb8aa3b, v8
	v_exp_f32_e32 v77, v76
	v_mul_f32_e32 v76, 0xbfb8aa3b, v9
	v_exp_f32_e32 v79, v76
	v_add_f32_e32 v75, 1.0, v75
	v_rcp_f32_e32 v76, v75
	v_add_f32_e32 v75, 1.0, v77
	v_rcp_f32_e32 v78, v75
	v_add_f32_e32 v75, 1.0, v79
	v_mul_f32_e32 v77, 0xbfb8aa3b, v2
	v_mul_f32_e32 v79, 0xbfb8aa3b, v3
	v_exp_f32_e32 v77, v77
	v_exp_f32_e32 v79, v79
	v_mul_f32_e32 v74, 0xbfb8aa3b, v6
	v_exp_f32_e32 v74, v74
	v_rcp_f32_e32 v80, v75
	v_add_f32_e32 v75, 1.0, v77
	v_add_f32_e32 v77, 1.0, v79
	v_mul_f32_e32 v79, 0xbfb8aa3b, v4
	v_exp_f32_e32 v79, v79
	v_mul_f32_e32 v81, 0xbfb8aa3b, v5
	v_exp_f32_e32 v81, v81
	v_add_f32_e32 v74, 1.0, v74
	v_rcp_f32_e32 v74, v74
	v_rcp_f32_e32 v75, v75
	v_rcp_f32_e32 v77, v77
	v_add_f32_e32 v79, 1.0, v79
	v_rcp_f32_e32 v79, v79
	v_add_f32_e32 v81, 1.0, v81
	v_rcp_f32_e32 v81, v81
	v_pk_fma_f32 v[74:75], v[74:75], s[0:1], v[148:149] op_sel_hi:[1,0,0]
	v_pk_fma_f32 v[76:77], v[76:77], s[0:1], v[148:149] op_sel_hi:[1,0,0]
	v_pk_fma_f32 v[78:79], v[78:79], s[0:1], v[148:149] op_sel_hi:[1,0,0]
	v_lshrrev_b32_e32 v74, 8, v74
	v_and_b32_e32 v76, 0xff00, v76
	v_lshrrev_b32_e32 v75, 8, v75
	v_and_b32_e32 v77, 0xff00, v77
	v_or_b32_sdwa v74, v74, v76 dst_sel:DWORD dst_unused:UNUSED_PAD src0_sel:BYTE_0 src1_sel:DWORD
	v_lshlrev_b32_e32 v76, 8, v79
	v_pk_fma_f32 v[80:81], v[80:81], s[0:1], v[148:149] op_sel_hi:[1,0,0]
	v_or_b32_sdwa v75, v75, v77 dst_sel:DWORD dst_unused:UNUSED_PAD src0_sel:BYTE_0 src1_sel:DWORD
	v_and_b32_e32 v76, 0xff0000, v76
	v_or_b32_e32 v75, v75, v76
	v_lshlrev_b32_e32 v76, 16, v81
	v_mul_f32_e32 v55, 0xbfb8aa3b, v55
	v_and_b32_e32 v76, 0xff000000, v76
	v_exp_f32_e32 v55, v55
	v_mul_f32_e32 v56, 0xbfb8aa3b, v56
	v_or_b32_e32 v75, v75, v76
	v_exp_f32_e32 v76, v56
	v_mul_f32_e32 v56, 0xbfb8aa3b, v57
	v_exp_f32_e32 v57, v56
	v_add_f32_e32 v55, 1.0, v55
	v_rcp_f32_e32 v56, v55
	v_add_f32_e32 v55, 1.0, v76
	v_mul_f32_e32 v34, 0xbfb8aa3b, v34
	v_mul_f32_e32 v54, 0xbfb8aa3b, v54
	v_rcp_f32_e32 v76, v55
	v_add_f32_e32 v55, 1.0, v57
	v_exp_f32_e32 v57, v34
	v_mul_f32_e32 v34, 0xbfb8aa3b, v35
	v_exp_f32_e32 v54, v54
	v_exp_f32_e32 v35, v34
	v_mul_f32_e32 v36, 0xbfb8aa3b, v36
	v_exp_f32_e32 v36, v36
	v_mul_f32_e32 v37, 0xbfb8aa3b, v37
	v_lshlrev_b32_e32 v77, 8, v78
	v_exp_f32_e32 v37, v37
	v_and_b32_e32 v77, 0xff0000, v77
	v_or_b32_e32 v74, v74, v77
	v_lshlrev_b32_e32 v77, 16, v80
	v_add_f32_e32 v54, 1.0, v54
	v_rcp_f32_e32 v34, v55
	v_add_f32_e32 v55, 1.0, v57
	v_add_f32_e32 v35, 1.0, v35
	v_and_b32_e32 v77, 0xff000000, v77
	v_rcp_f32_e32 v54, v54
	v_rcp_f32_e32 v55, v55
	v_rcp_f32_e32 v57, v35
	v_add_f32_e32 v35, 1.0, v36
	v_or_b32_e32 v74, v74, v77
	v_rcp_f32_e32 v77, v35
	v_add_f32_e32 v35, 1.0, v37
	v_rcp_f32_e32 v35, v35
	v_pk_fma_f32 v[36:37], v[54:55], s[0:1], v[148:149] op_sel_hi:[1,0,0]
	v_pk_fma_f32 v[54:55], v[56:57], s[0:1], v[148:149] op_sel_hi:[1,0,0]
	v_pk_fma_f32 v[56:57], v[76:77], s[0:1], v[148:149] op_sel_hi:[1,0,0]
	v_lshrrev_b32_e32 v37, 8, v37
	v_lshrrev_b32_e32 v36, 8, v36
	v_and_b32_e32 v55, 0xff00, v55
	v_and_b32_e32 v54, 0xff00, v54
	v_pk_fma_f32 v[34:35], v[34:35], s[0:1], v[148:149] op_sel_hi:[1,0,0]
	v_or_b32_sdwa v37, v37, v55 dst_sel:DWORD dst_unused:UNUSED_PAD src0_sel:BYTE_0 src1_sel:DWORD
	v_or_b32_sdwa v36, v36, v54 dst_sel:DWORD dst_unused:UNUSED_PAD src0_sel:BYTE_0 src1_sel:DWORD
	v_lshlrev_b32_e32 v54, 8, v57
	v_lshlrev_b32_e32 v55, 8, v56
	v_and_b32_e32 v54, 0xff0000, v54
	v_and_b32_e32 v55, 0xff0000, v55
	v_lshlrev_b32_e32 v35, 16, v35
	v_lshlrev_b32_e32 v34, 16, v34
	v_or_b32_e32 v37, v37, v54
	v_or_b32_e32 v36, v36, v55
	v_and_b32_e32 v35, 0xff000000, v35
	v_and_b32_e32 v34, 0xff000000, v34
	v_or_b32_e32 v77, v37, v35
	v_or_b32_e32 v76, v36, v34
	global_store_dwordx4 v[150:151], v[156:159], off sc1 nt
	global_store_dwordx4 v[150:151], v[122:125], off offset:1024 sc1 nt
	global_store_dwordx4 v[150:151], v[114:117], off offset:2048 sc1 nt
	global_store_dwordx4 v[150:151], v[106:109], off offset:3072 sc1 nt
	global_store_dwordx4 v[90:91], v[92:95], off offset:1024 sc1 nt
	global_store_dwordx4 v[90:91], v[82:85], off offset:2048 sc1 nt
	global_store_dwordx4 v[90:91], v[74:77], off offset:3072 sc1 nt

.LBB0_116:
	s_and_saveexec_b64 s[0:1], s[22:23]
	s_cbranch_execz .LBB0_118
	v_or_b32_e32 v36, 16, v146
	v_ashrrev_i32_e32 v147, 31, v146
	v_ashrrev_i32_e32 v37, 31, v36
	v_lshlrev_b64 v[34:35], 6, v[146:147]
	v_lshlrev_b64 v[36:37], 6, v[36:37]
	v_lshl_add_u64 v[34:35], v[140:141], 0, v[34:35]
	v_lshl_add_u64 v[36:37], v[140:141], 0, v[36:37]
	global_store_dwordx4 v[34:35], v[70:73], off sc1 nt
	global_store_dwordx4 v[34:35], v[66:69], off offset:16 sc1 nt
	global_store_dwordx4 v[36:37], v[62:65], off sc1 nt
	global_store_dwordx4 v[36:37], v[58:61], off offset:16 sc1 nt
	v_or_b32_e32 v36, 32, v146
	v_ashrrev_i32_e32 v37, 31, v36
	v_lshlrev_b64 v[36:37], 6, v[36:37]
	v_lshl_add_u64 v[36:37], v[140:141], 0, v[36:37]
	global_store_dwordx4 v[36:37], v[50:53], off sc1 nt
	global_store_dwordx4 v[36:37], v[46:49], off offset:16 sc1 nt
	v_or_b32_e32 v36, 48, v146
	v_ashrrev_i32_e32 v37, 31, v36
	v_lshlrev_b64 v[36:37], 6, v[36:37]
	v_lshl_add_u64 v[36:37], v[140:141], 0, v[36:37]
	s_movk_i32 s18, 0x2000
	global_store_dwordx4 v[36:37], v[42:45], off sc1 nt
	global_store_dwordx4 v[36:37], v[38:41], off offset:16 sc1 nt
	s_mov_b64 s[30:31], 0x2000
	v_lshl_add_u64 v[36:37], v[34:35], 0, s[30:31]
	v_add_co_u32_e32 v38, vcc, s18, v34
	s_mov_b64 s[30:31], 0x2400
	s_nop 0
	v_addc_co_u32_e32 v39, vcc, 0, v35, vcc
	global_store_dwordx4 v[38:39], v[30:33], off sc1 nt
	global_store_dwordx4 v[36:37], v[26:29], off offset:16 sc1 nt
	s_nop 1
	v_lshl_add_u64 v[26:27], v[34:35], 0, s[30:31]
	s_mov_b64 s[30:31], 0x2800
	global_store_dwordx4 v[38:39], v[22:25], off offset:1024 sc1 nt
	global_store_dwordx4 v[26:27], v[18:21], off offset:16 sc1 nt
	s_nop 1
	v_lshl_add_u64 v[18:19], v[34:35], 0, s[30:31]
	s_mov_b64 s[30:31], 0x2c00
	global_store_dwordx4 v[38:39], v[14:17], off offset:2048 sc1 nt
	global_store_dwordx4 v[18:19], v[10:13], off offset:16 sc1 nt
	s_nop 1
	v_lshl_add_u64 v[10:11], v[34:35], 0, s[30:31]
	global_store_dwordx4 v[38:39], v[6:9], off offset:3072 sc1 nt
	global_store_dwordx4 v[10:11], v[2:5], off offset:16 sc1 nt
